# adds: last-arriving XCD leader no longer issues (and waits on) the now-unused TOPGEN atomic before publishing XGEN
# speedup vs baseline: 1.0045x; 1.0045x over previous
; DI unsigned xb_ld(unsigned* p) { return __hip_atomic_load(p, __ATOMIC_RELAXED, __HIP_MEMORY_SCOPE_AGENT); }
; DI unsigned xb_add(unsigned* p, unsigned v) { return __hip_atomic_fetch_add(p, v, __ATOMIC_RELAXED, __HIP_MEMORY_SCOPE_AGENT); }
; #define XB_SPIN(cond, bar) do { unsigned _sp = 0; while (cond) { __builtin_amdgcn_s_sleep(1); \
;     if ((++_sp & 255u) == 0u) { if (xb_ld(&(bar)[XB_TMO])) break; if (_sp > XB_SPIN_CAP) { atomicAdd(&(bar)[XB_TMO], 1u); break; } } } } while (0)
; DI void xcd_barrier(unsigned* bar, volatile LAS unsigned* st) {
;     ...
;     if (old + 1u == (gen + 1u) * nloc) {
;       __builtin_amdgcn_fence(__ATOMIC_RELEASE, "agent");
;       asm volatile("s_waitcnt vmcnt(0)" ::: "memory");
;       const unsigned og = xb_add(&bar[XB_TOP], 1u);
;       const unsigned tg = og / nx;
;       if (og + 1u == (tg + 1u) * nx) xb_add(&bar[XB_TOPGEN], 1u);
;       else XB_SPIN(xb_ld(&bar[XB_TOPGEN]) == tg, bar);
.LBB0_363:
	s_andn2_saveexec_b64 s[0:1], s[0:1]
	s_cbranch_execz .LBB0_379
	v_mov_b32_e32 v2, s58
	v_add_co_u32_e32 v2, vcc, 0x22f23000, v2
	v_mov_b32_e32 v3, s59
	buffer_wbl2 sc1
	s_waitcnt vmcnt(0)
	v_addc_co_u32_e32 v3, vcc, 0, v3, vcc
	flat_atomic_add v2, v[2:3], v187 offset:1024 sc0
	v_cvt_f32_u32_e32 v3, v0
	v_sub_u32_e32 v4, 0, v0
	s_mov_b64 s[6:7], 0
	v_rcp_iflag_f32_e32 v3, v3
	s_nop 0
	v_mul_f32_e32 v3, 0x4f7ffffe, v3
	v_cvt_u32_f32_e32 v3, v3
	v_mul_lo_u32 v4, v4, v3
	v_mul_hi_u32 v4, v3, v4
	v_add_u32_e32 v3, v3, v4
	s_waitcnt vmcnt(0) lgkmcnt(0)
	v_mul_hi_u32 v3, v2, v3
	v_mul_lo_u32 v4, v3, v0
	v_sub_u32_e32 v4, v2, v4
	v_cmp_ge_u32_e32 vcc, v4, v0
	v_add_u32_e32 v5, 1, v3
	s_nop 0
	v_cndmask_b32_e32 v3, v3, v5, vcc
	v_sub_u32_e32 v5, v4, v0
	v_cndmask_b32_e32 v4, v4, v5, vcc
	v_cmp_ge_u32_e32 vcc, v4, v0
	v_add_u32_e32 v4, 1, v3
	v_add_u32_e32 v5, 1, v2
	v_cndmask_b32_e32 v4, v3, v4, vcc
	v_mad_u64_u32 v[2:3], s[0:1], v0, v4, v[0:1]
	v_mov_b32_e32 v6, v2
	s_add_u32 s0, s58, 0x22f23500
	s_addc_u32 s1, s59, 0
	v_cmp_ne_u32_e32 vcc, v5, v2
	v_mov_b64_e32 v[2:3], s[0:1]
	s_and_saveexec_b64 s[4:5], vcc
	s_cbranch_execz .LBB0_376
	v_mov_b64_e32 v[2:3], s[0:1]
	global_load_dword v0, v[2:3], off offset:-256 sc1
	s_mov_b64 s[10:11], 0
	s_waitcnt vmcnt(0) lgkmcnt(0)
	v_cmp_lt_u32_e32 vcc, v0, v6
	s_and_saveexec_b64 s[8:9], vcc
	s_cbranch_execz .LBB0_375
	s_add_u32 s6, s58, 0x22f20200
	s_addc_u32 s7, s59, 0
	s_mov_b32 s22, 1
	s_branch .LBB0_368

; DI unsigned xb_ld(unsigned* p) { return __hip_atomic_load(p, __ATOMIC_RELAXED, __HIP_MEMORY_SCOPE_AGENT); }
; DI unsigned xb_add(unsigned* p, unsigned v) { return __hip_atomic_fetch_add(p, v, __ATOMIC_RELAXED, __HIP_MEMORY_SCOPE_AGENT); }
; #define XB_SPIN(cond, bar) do { unsigned _sp = 0; while (cond) { __builtin_amdgcn_s_sleep(1); \
;     if ((++_sp & 255u) == 0u) { if (xb_ld(&(bar)[XB_TMO])) break; if (_sp > XB_SPIN_CAP) { atomicAdd(&(bar)[XB_TMO], 1u); break; } } } } while (0)
; DI void xcd_barrier(unsigned* bar, volatile LAS unsigned* st) {
;     ...
;     if (old + 1u == (gen + 1u) * nloc) {
;       __builtin_amdgcn_fence(__ATOMIC_RELEASE, "agent");
;       asm volatile("s_waitcnt vmcnt(0)" ::: "memory");
;       const unsigned og = xb_add(&bar[XB_TOP], 1u);
;       const unsigned tg = og / nx;
;       if (og + 1u == (tg + 1u) * nx) xb_add(&bar[XB_TOPGEN], 1u);
;       else XB_SPIN(xb_ld(&bar[XB_TOPGEN]) == tg, bar);
.LBB0_861:
	s_andn2_saveexec_b64 s[0:1], s[0:1]
	s_cbranch_execz .LBB0_321
	v_mov_b32_e32 v2, s40
	v_add_co_u32_e32 v2, vcc, 0x22f23000, v2
	v_mov_b32_e32 v3, s41
	buffer_wbl2 sc1
	s_waitcnt vmcnt(0)
	v_addc_co_u32_e32 v3, vcc, 0, v3, vcc
	flat_atomic_add v2, v[2:3], v187 offset:1024 sc0
	v_cvt_f32_u32_e32 v3, v0
	v_sub_u32_e32 v4, 0, v0
	s_mov_b64 s[6:7], 0
	v_rcp_iflag_f32_e32 v3, v3
	s_nop 0
	v_mul_f32_e32 v3, 0x4f7ffffe, v3
	v_cvt_u32_f32_e32 v3, v3
	v_mul_lo_u32 v4, v4, v3
	v_mul_hi_u32 v4, v3, v4
	v_add_u32_e32 v3, v3, v4
	s_waitcnt vmcnt(0) lgkmcnt(0)
	v_mul_hi_u32 v3, v2, v3
	v_mul_lo_u32 v4, v3, v0
	v_sub_u32_e32 v4, v2, v4
	v_cmp_ge_u32_e32 vcc, v4, v0
	v_add_u32_e32 v5, 1, v3
	s_nop 0
	v_cndmask_b32_e32 v3, v3, v5, vcc
	v_sub_u32_e32 v5, v4, v0
	v_cndmask_b32_e32 v4, v4, v5, vcc
	v_cmp_ge_u32_e32 vcc, v4, v0
	v_add_u32_e32 v4, 1, v3
	v_add_u32_e32 v5, 1, v2
	v_cndmask_b32_e32 v4, v3, v4, vcc
	v_mad_u64_u32 v[2:3], s[0:1], v0, v4, v[0:1]
	v_mov_b32_e32 v6, v2
	s_add_u32 s0, s40, 0x22f23500
	s_addc_u32 s1, s41, 0
	v_cmp_ne_u32_e32 vcc, v5, v2
	v_mov_b64_e32 v[2:3], s[0:1]
	s_and_saveexec_b64 s[4:5], vcc
	s_cbranch_execz .LBB0_874
	v_mov_b64_e32 v[2:3], s[0:1]
	global_load_dword v0, v[2:3], off offset:-256 sc1
	s_mov_b64 s[10:11], 0
	s_waitcnt vmcnt(0) lgkmcnt(0)
	v_cmp_lt_u32_e32 vcc, v0, v6
	s_and_saveexec_b64 s[8:9], vcc
	s_cbranch_execz .LBB0_873
	s_add_u32 s6, s40, 0x22f20200
	s_addc_u32 s7, s41, 0
	s_mov_b32 s22, 1
	s_branch .LBB0_866
